# cand G + union of hand-off trims: duplicate lgkmcnt(0) after barrier removed in the mainloops, barrier leader releases followers before its own invalidate, P6 skinny task reuses the A operand
# baseline (speedup 1.0000x reference)
.LBB0_1146:
	s_add_i32 s16, s16, 1
	s_cmp_lt_i32 s16, s14
	s_cselect_b64 s[8:9], -1, 0
	s_cmp_ge_i32 s16, s14
	s_cbranch_scc1 .LBB0_1148
	s_and_b32 s19, s10, 0x60
	s_add_i32 s18, s40, s41
	v_or_b32_e32 v0, s19, v138
	s_ashr_i32 s18, s18, 2
	v_lshlrev_b32_e32 v0, 11, v0
	v_lshl_add_u64 v[86:87], v[130:131], 0, v[0:1]
	s_ashr_i32 s19, s18, 31
	s_lshl_b64 s[18:19], s[18:19], 16
	v_add_co_u32_e32 v88, vcc, 0x8000, v86
	v_lshl_add_u64 v[114:115], v[132:133], 0, s[18:19]
	s_nop 0
	v_addc_co_u32_e32 v89, vcc, 0, v87, vcc
	v_add_co_u32_e32 v116, vcc, 0x8000, v114
	s_nop 1
	v_addc_co_u32_e32 v117, vcc, 0, v115, vcc
	global_load_dwordx4 v[110:113], v[114:115], off
	global_load_dwordx4 v[106:109], v[114:115], off offset:64
	global_load_dwordx4 v[102:105], v[116:117], off
	global_load_dwordx4 v[98:101], v[116:117], off offset:64
	global_load_dwordx4 v[126:129], v[114:115], off offset:128
	global_load_dwordx4 v[122:125], v[114:115], off offset:192
	global_load_dwordx4 v[118:121], v[116:117], off offset:128
	global_load_dwordx4 v[114:117], v[116:117], off offset:192
	s_and_b32 s100, s94, 3
	s_cmp_lg_u32 s100, 0
	s_cbranch_scc0 .Lp6sk_noAld
	global_load_dwordx4 v[66:69], v[86:87], off
	global_load_dwordx4 v[78:81], v[86:87], off offset:64
	global_load_dwordx4 v[74:77], v[88:89], off
	global_load_dwordx4 v[70:73], v[88:89], off offset:64
	global_load_dwordx4 v[82:85], v[86:87], off offset:128
	global_load_dwordx4 v[94:97], v[86:87], off offset:192
	global_load_dwordx4 v[90:93], v[88:89], off offset:128
	global_load_dwordx4 v[86:89], v[88:89], off offset:192
.Lp6sk_noAld:
.LBB0_1148:
	s_waitcnt vmcnt(11)
	v_mfma_f32_16x16x32_bf16 v[144:147], v[46:49], v[2:5], 0
	v_add_u32_e32 v0, s15, v141
	s_andn2_b64 vcc, exec, s[6:7]
	s_waitcnt vmcnt(9)
	v_mfma_f32_16x16x32_bf16 v[148:151], v[38:41], v[2:5], 0
	v_mfma_f32_16x16x32_bf16 v[152:155], v[46:49], v[10:13], 0
	v_mfma_f32_16x16x32_bf16 v[156:159], v[38:41], v[10:13], 0
	v_mfma_f32_16x16x32_bf16 v[144:147], v[42:45], v[14:17], v[144:147]
	s_waitcnt vmcnt(8)
	v_mfma_f32_16x16x32_bf16 v[148:151], v[34:37], v[14:17], v[148:151]
	v_mfma_f32_16x16x32_bf16 v[152:155], v[42:45], v[6:9], v[152:155]
	v_mfma_f32_16x16x32_bf16 v[156:159], v[34:37], v[6:9], v[156:159]
	s_waitcnt vmcnt(3)
	v_mfma_f32_16x16x32_bf16 v[144:147], v[62:65], v[18:21], v[144:147]
	s_waitcnt vmcnt(1)
	v_mfma_f32_16x16x32_bf16 v[148:151], v[54:57], v[18:21], v[148:151]
	v_mfma_f32_16x16x32_bf16 v[152:155], v[62:65], v[26:29], v[152:155]
	v_mfma_f32_16x16x32_bf16 v[156:159], v[54:57], v[26:29], v[156:159]
	v_mfma_f32_16x16x32_bf16 v[144:147], v[58:61], v[30:33], v[144:147]
	s_waitcnt vmcnt(0)
	v_mfma_f32_16x16x32_bf16 v[148:151], v[50:53], v[30:33], v[148:151]
	v_mfma_f32_16x16x32_bf16 v[152:155], v[58:61], v[22:25], v[152:155]
	v_mfma_f32_16x16x32_bf16 v[156:159], v[50:53], v[22:25], v[156:159]
	s_nop 3
	ds_write2st64_b32 v0, v144, v145 offset1:1
	ds_write2st64_b32 v0, v146, v147 offset0:2 offset1:3
	ds_write2st64_b32 v0, v148, v149 offset0:4 offset1:5
	ds_write2st64_b32 v0, v150, v151 offset0:6 offset1:7
	ds_write2st64_b32 v0, v152, v153 offset0:8 offset1:9
	ds_write2st64_b32 v0, v154, v155 offset0:10 offset1:11
	ds_write2st64_b32 v0, v156, v157 offset0:12 offset1:13
	ds_write2st64_b32 v0, v158, v159 offset0:14 offset1:15
	s_waitcnt lgkmcnt(0)
	s_barrier
	s_cbranch_vccnz .LBB0_1150
	v_add_u32_e32 v0, s42, v141
	ds_read2st64_b32 v[144:145], v0 offset1:1
	s_and_b32 s18, s12, 0xffffffe0
	v_add_u32_e32 v136, s18, v140
	s_waitcnt lgkmcnt(0)
	v_add_f32_e32 v135, 0, v144
	v_add_f32_e32 v137, 0, v145
	ds_read2st64_b32 v[144:145], v0 offset0:2 offset1:3
	s_waitcnt lgkmcnt(0)
	v_add_f32_e32 v143, 0, v144
	v_add_f32_e32 v146, 0, v145
	ds_read2st64_b32 v[144:145], v0 offset0:16 offset1:17
	s_waitcnt lgkmcnt(0)
	v_add_f32_e32 v135, v135, v144
	v_add_f32_e32 v137, v137, v145
	ds_read2st64_b32 v[144:145], v0 offset0:18 offset1:19
	s_waitcnt lgkmcnt(0)
	v_add_f32_e32 v143, v143, v144
	v_add_f32_e32 v146, v146, v145
	ds_read2st64_b32 v[144:145], v0 offset0:32 offset1:33
	s_waitcnt lgkmcnt(0)
	v_add_f32_e32 v135, v135, v144
	v_add_f32_e32 v137, v137, v145
	ds_read2st64_b32 v[144:145], v0 offset0:34 offset1:35
	s_waitcnt lgkmcnt(0)
	v_add_f32_e32 v143, v143, v144
	v_add_f32_e32 v146, v146, v145
	ds_read2st64_b32 v[144:145], v0 offset0:48 offset1:49
	s_waitcnt lgkmcnt(0)
	v_add_f32_e32 v135, v135, v144
	v_add_f32_e32 v137, v137, v145
	ds_read2st64_b32 v[144:145], v0 offset0:50 offset1:51
	s_waitcnt lgkmcnt(0)
	v_add_f32_e32 v143, v143, v144
	v_add_f32_e32 v146, v146, v145
	ds_read2st64_b32 v[144:145], v0 offset0:64 offset1:65
	s_waitcnt lgkmcnt(0)
	v_add_f32_e32 v135, v135, v144
	v_add_f32_e32 v137, v137, v145
	ds_read2st64_b32 v[144:145], v0 offset0:66 offset1:67
	s_waitcnt lgkmcnt(0)
	v_add_f32_e32 v143, v143, v144
	v_add_f32_e32 v146, v146, v145
	ds_read2st64_b32 v[144:145], v0 offset0:80 offset1:81
	s_waitcnt lgkmcnt(0)
	v_add_f32_e32 v135, v135, v144
	v_add_f32_e32 v137, v137, v145
	ds_read2st64_b32 v[144:145], v0 offset0:82 offset1:83
	s_waitcnt lgkmcnt(0)
	v_add_f32_e32 v143, v143, v144
	v_add_f32_e32 v146, v146, v145
	ds_read2st64_b32 v[144:145], v0 offset0:96 offset1:97
	s_waitcnt lgkmcnt(0)
	v_add_f32_e32 v135, v135, v144
	v_add_f32_e32 v137, v137, v145
	ds_read2st64_b32 v[144:145], v0 offset0:98 offset1:99
	s_waitcnt lgkmcnt(0)
	v_add_f32_e32 v143, v143, v144
	v_add_f32_e32 v146, v146, v145
	ds_read2st64_b32 v[144:145], v0 offset0:112 offset1:113
	s_waitcnt lgkmcnt(0)
	v_add_f32_e32 v135, v135, v144
	v_add_f32_e32 v137, v137, v145
	ds_read2st64_b32 v[144:145], v0 offset0:114 offset1:115
	v_mul_f32_e32 v135, v142, v135
	v_max_f32_e32 v135, 0, v135
	v_mul_f32_e32 v137, v142, v137
	v_mul_f32_e32 v135, v135, v135
	v_max_f32_e32 v137, 0, v137
	s_waitcnt lgkmcnt(0)
	v_add_f32_e32 v0, v143, v144
	v_mul_f32_e32 v137, v137, v137
	v_cvt_pk_bf16_f32 v144, v135, v137
	v_ashrrev_i32_e32 v135, 31, v134
	v_lshlrev_b64 v[134:135], 13, v[134:135]
	v_lshl_add_u64 v[134:135], s[0:1], 0, v[134:135]
	v_ashrrev_i32_e32 v137, 31, v136
	v_add_f32_e32 v143, v146, v145
	v_lshl_add_u64 v[134:135], v[136:137], 1, v[134:135]
	v_mul_f32_e32 v0, v142, v0
	v_mul_f32_e32 v143, v142, v143
	v_add_co_u32_e32 v134, vcc, 0x1d4b3000, v134
	v_max_f32_e32 v0, 0, v0
	v_max_f32_e32 v143, 0, v143
	v_addc_co_u32_e32 v135, vcc, 0, v135, vcc
	v_mul_f32_e32 v0, v0, v0
	v_mul_f32_e32 v143, v143, v143
	v_cvt_pk_bf16_f32 v145, v0, v143
	global_store_dwordx2 v[134:135], v[144:145], off offset:3840
.LBB0_1150:
	s_waitcnt lgkmcnt(0)
	s_barrier
	s_andn2_b64 vcc, exec, s[8:9]
	s_cbranch_vccnz .LBB0_1143
	v_mov_b64_e32 v[50:51], v[114:115]
	v_mov_b64_e32 v[54:55], v[118:119]
	v_mov_b64_e32 v[34:35], v[98:99]
	v_mov_b64_e32 v[38:39], v[102:103]
	v_mov_b64_e32 v[58:59], v[122:123]
	v_mov_b64_e32 v[62:63], v[126:127]
	v_mov_b64_e32 v[42:43], v[106:107]
	v_mov_b64_e32 v[46:47], v[110:111]
	v_mov_b64_e32 v[52:53], v[116:117]
	v_mov_b64_e32 v[56:57], v[120:121]
	v_mov_b64_e32 v[36:37], v[100:101]
	v_mov_b64_e32 v[40:41], v[104:105]
	v_mov_b64_e32 v[60:61], v[124:125]
	v_mov_b64_e32 v[64:65], v[128:129]
	v_mov_b64_e32 v[44:45], v[108:109]
	v_mov_b64_e32 v[48:49], v[112:113]
	s_and_b32 s100, s94, 3
	s_cmp_lg_u32 s100, 0
	s_cbranch_scc0 .Lp6sk_noAcp
	v_mov_b64_e32 v[22:23], v[86:87]
	v_mov_b64_e32 v[26:27], v[90:91]
	v_mov_b64_e32 v[6:7], v[70:71]
	v_mov_b64_e32 v[10:11], v[74:75]
	v_mov_b64_e32 v[30:31], v[94:95]
	v_mov_b64_e32 v[18:19], v[82:83]
	v_mov_b64_e32 v[14:15], v[78:79]
	v_mov_b64_e32 v[2:3], v[66:67]
	v_mov_b64_e32 v[24:25], v[88:89]
	v_mov_b64_e32 v[28:29], v[92:93]
	v_mov_b64_e32 v[8:9], v[72:73]
	v_mov_b64_e32 v[12:13], v[76:77]
	v_mov_b64_e32 v[32:33], v[96:97]
	v_mov_b64_e32 v[20:21], v[84:85]
	v_mov_b64_e32 v[16:17], v[80:81]
	v_mov_b64_e32 v[4:5], v[68:69]
.Lp6sk_noAcp:
	s_branch .LBB0_1143
.LBB0_1152:
	s_waitcnt vmcnt(0)
	s_waitcnt lgkmcnt(0)
	s_barrier
	s_mov_b64 s[0:1], exec
	v_readlane_b32 s2, v252, 0
	v_readlane_b32 s3, v252, 1
	s_and_b64 s[2:3], s[0:1], s[2:3]
	s_mov_b64 exec, s[2:3]
	s_cbranch_execz .LBB0_1204
	v_readlane_b32 s2, v253, 23
	s_mov_b32 s8, s78
	s_waitcnt vmcnt(0) expcnt(0) lgkmcnt(0)
	v_mov_b32_e32 v0, s2
	ds_read_b32 v3, v0
	v_readlane_b32 s2, v253, 24
	s_waitcnt lgkmcnt(0)
	v_cmp_ne_u32_e32 vcc, 0, v3
	v_mov_b32_e32 v0, s2
	ds_read_b32 v2, v0
	s_cbranch_vccnz .LBB0_1168
	s_mov_b32 s9, 1
	s_branch .LBB0_1156
